# S5-out item order made XCD-aware: the 16 items sharing activation cache lines run on one XCD together
# baseline (speedup 1.0000x reference)
; DEV int vbid() { return (int)blockIdx.x * 2 + vbsel(); }
; DEV int vgrid() { return (int)gridDim.x * 2; }
; DEV int rounds_of(int total) { const int vg = vgrid(); int r = 0; for (int t = 0; t < total; t += vg) ++r; return r; }
; DEV void ph_attn(const P& p, int l, bool need, char* smem) {
;     ...
;     for (int r_ = 0, nr_ = rounds_of(32 * nmt * 4); r_ < nr_; ++r_) { int t = vbid() + r_ * vgrid(); t = t < (32 * nmt * 4) ? t : (32 * nmt * 4) - 1;
;       const int g = t / (nmt * 4), mt = (t % (nmt * 4)) >> 2, nt = t & 3;
.LBB0_118:
	v_readfirstlane_b32 s4, v201
	s_lshr_b32 s24, s4, 8
	s_mul_i32 s4, s23, s91
	v_readlane_b32 s5, v253, 2
	s_add_i32 s4, s4, s5
	s_add_i32 s4, s4, s24
	s_cmpk_lg_i32 s54, 0x100
	s_cbranch_scc1 .Ls5map_done
	s_and_b32 s5, s73, 7
	s_lshr_b32 s6, s73, 3
	s_lshl_b32 s6, s6, 1
	s_add_i32 s6, s6, s24
	s_lshr_b32 s7, s6, 4
	s_lshl_b32 s7, s7, 3
	s_add_i32 s7, s7, s5
	s_lshl_b32 s8, s23, 5
	s_add_i32 s7, s7, s8
	s_lshr_b32 s8, s45, 2
	s_lshl_b32 s9, s8, 3
	s_cmp_ge_u32 s7, s9
	s_cbranch_scc1 .Ls5map_inv
	s_lshr_b32 s9, s7, 3
	s_cmp_eq_u32 s8, 9
	s_cbranch_scc0 .Ls5map_q
	s_mul_i32 s9, s7, 0x1c72
	s_lshr_b32 s9, s9, 16
.Ls5map_q:
	s_mul_i32 s10, s9, s8
	s_sub_i32 s10, s7, s10
	s_lshl_b32 s9, s9, 2
	s_bfe_u32 s11, s6, 0x20002
	s_add_i32 s9, s9, s11
	s_mul_i32 s9, s9, s8
	s_add_i32 s9, s9, s10
	s_lshl_b32 s9, s9, 2
	s_and_b32 s6, s6, 3
	s_add_i32 s4, s9, s6
	s_branch .Ls5map_done
.Ls5map_inv:
	s_mov_b32 s4, 0x7fffffff
; DEV int vboff() { return vbsel() * 81920; }
; #define GLOAD(RA, RB, kt) { const int k_ = (kt) * 64 + lc * 8; const long ko_ = (long)(k_ >> a.segshift) * a.segstride + (k_ & segmask); \
;     _Pragma("unroll") for (int i = 0; i < 4; ++i) RA[i] = *(const u32x4*)(ap[i] + ko_); \
;     _Pragma("unroll") for (int i = 0; i < NBL; ++i) RB[i] = *(const u32x4*)(bp + (long)(32 * i) * ldb + (kt) * 64); }
; #define LSTORE(RA, RB, buf) { char* s_ = smem + (buf) * STAGE; \
;     _Pragma("unroll") for (int i = 0; i < 4; ++i) *(u32x4*)(s_ + wofs + i * 4096) = RA[i]; \
;     _Pragma("unroll") for (int i = 0; i < NBL; ++i) *(u32x4*)(s_ + ABYTES + wofs + i * 4096) = RB[i]; }
; #define BAR() { asm volatile("s_waitcnt lgkmcnt(0)" ::: "memory"); __builtin_amdgcn_s_barrier(); asm volatile("" ::: "memory"); }
; template <int WN, bool SWAP>
; DEV void gemm_core(f32x4 (&acc)[4][WN], const ASrc& a, const bf16_t* __restrict__ Bt, long ldb, int K, char* smem) {
;     ...
;   for (int i = 0; i < 4; ++i) { int r = a.row0 + lrow + 32 * i; r = r < a.rmax ? r : a.rmax - 1; ap[i] = a.p + (long)r * a.lda; }
;   const bf16_t* bp = Bt + (long)lrow * ldb + lc * 8;
;   const int vo = vboff();
;   const int wofs = vo + lrow * 128 + ((lc ^ ((lrow >> 1) & 7)) << 4);
;   u32x4 ra0[4], rb0[NBL], ra1[4], rb1[NBL];
;   const int aoff = vo + (wm * 64 + l15) * 128, boff = vo + ABYTES + (wn * 16 * WN + l15) * 128, sx = l15 >> 1;
;   int nk = K >> 6; asm volatile("" : "+s"(nk));
;     ...
;   __builtin_amdgcn_sched_barrier(0);
;   GLOAD(ra0, rb0, 0); GLOAD(ra1, rb1, 1); LSTORE(ra0, rb0, 0); BAR();
; DEV void ph_attn(const P& p, int l, bool need, char* smem) {
;     ...
;       const int g = t / (nmt * 4), mt = (t % (nmt * 4)) >> 2, nt = t & 3;
;       f32x4 acc[4][4]; zero_acc<4>(acc);
;       ASrc a; a.p = Z + ZS5 + g * 16; a.lda = 32 * LDZ; a.row0 = mt * 128; a.rmax = rmax; a.segshift = 4; a.segstride = LDZ;
;       gemm_core<4, true>(acc, a, Mt + ((size_t)g * 512 + nt * 128) * 512, 512, 512, smem);
.Ls5map_done:
	s_min_i32 s11, s4, s41
	s_abs_i32 s5, s11
	s_mul_hi_u32 s6, s5, s49
	s_mul_i32 s7, s6, s45
	s_sub_i32 s5, s5, s7
	s_ashr_i32 s4, s11, 31
	s_add_i32 s7, s6, 1
	s_sub_i32 s8, s5, s45
	s_cmp_ge_u32 s5, s45
	s_cselect_b32 s6, s7, s6
	s_cselect_b32 s5, s8, s5
	s_add_i32 s7, s6, 1
	s_cmp_ge_u32 s5, s45
	s_cselect_b32 s5, s7, s6
	s_xor_b32 s5, s5, s4
	s_sub_i32 s6, s5, s4
	s_mul_i32 s4, s6, s45
	s_sub_i32 s7, s11, s4
	s_lshl_b32 s4, s6, 4
	s_ashr_i32 s5, s4, 31
	s_lshl_b64 s[4:5], s[4:5], 1
	s_add_u32 s12, s21, s4
	s_addc_u32 s13, s22, s5
	s_lshl_b32 s7, s7, 5
	s_and_b32 s10, s7, 0xffffff80
	s_ashr_i32 s7, s6, 31
	v_mov_b32 v8, v238
	s_lshl_b64 s[8:9], s[6:7], 9
	v_ashrrev_i32_e32 v10, 3, v8
	s_lshl_b32 s7, s11, 7
	v_add_u32_e32 v9, s10, v10
	s_and_b32 s11, s7, 0x180
	v_min_i32_e32 v0, s48, v9
	v_add_u32_e32 v2, 32, v9
	v_add_u32_e32 v4, 64, v9
	v_add_u32_e32 v9, 0x60, v9
	s_or_b32 s8, s8, s11
	v_mov_b64_e32 v[6:7], s[12:13]
	v_min_i32_e32 v2, s48, v2
	v_min_i32_e32 v4, s48, v4
	v_min_i32_e32 v9, s48, v9
	s_lshl_b64 s[14:15], s[8:9], 10
	v_mad_i64_i32 v[0:1], s[12:13], v0, s37, v[6:7]
	v_mad_i64_i32 v[2:3], s[12:13], v2, s37, v[6:7]
	v_mad_i64_i32 v[4:5], s[12:13], v4, s37, v[6:7]
	v_mad_i64_i32 v[6:7], s[12:13], v9, s37, v[6:7]
	v_lshlrev_b32_e32 v9, 3, v8
	s_add_u32 s14, s17, s14
	v_and_b32_e32 v145, 56, v9
	s_mul_i32 s12, s24, 0x14000
	v_lshlrev_b32_e32 v12, 4, v8
	s_mov_b32 s7, 8
	s_addc_u32 s15, s18, s15
	v_ashrrev_i32_e32 v11, 31, v10
	v_xor_b32_e32 v24, v12, v8
	v_bfe_u32 v12, v9, 4, 2
	v_lshlrev_b64 v[20:21], 10, v[10:11]
	v_mul_u32_u24_e32 v12, 0xb00, v12
	v_lshl_add_u64 v[20:21], s[14:15], 0, v[20:21]
	v_lshlrev_b32_e32 v22, 1, v145
	v_mov_b32_e32 v23, v41
	v_and_b32_e32 v9, 8, v9
	v_lshlrev_b32_e32 v12, 1, v12
	v_mov_b32_e32 v13, v41
	v_lshl_add_u64 v[134:135], v[20:21], 0, v[22:23]
	s_mov_b32 s13, 0x8000
	v_lshl_add_u64 v[14:15], v[0:1], 0, v[12:13]
	v_lshlrev_b32_e32 v40, 1, v9
	v_lshl_add_u64 v[16:17], v[2:3], 0, v[12:13]
	v_lshl_add_u64 v[18:19], v[4:5], 0, v[12:13]
	v_lshl_add_u64 v[12:13], v[6:7], 0, v[12:13]
	v_lshl_add_u32 v9, v10, 7, s12
	v_add_co_u32_e32 v10, vcc, s13, v134
	v_lshl_add_u64 v[12:13], v[12:13], 0, v[40:41]
	s_nop 0
	v_addc_co_u32_e32 v11, vcc, 0, v135, vcc
	s_mov_b32 s13, 0x10000
	global_load_dwordx4 v[80:83], v[12:13], off
	global_load_dwordx4 v[88:91], v[10:11], off
	v_add_co_u32_e32 v10, vcc, s13, v134
	v_lshl_add_u64 v[14:15], v[14:15], 0, v[40:41]
	s_nop 0
	v_addc_co_u32_e32 v11, vcc, 0, v135, vcc
	s_mov_b32 s13, 0x18000
	global_load_dwordx4 v[68:71], v[14:15], off
	global_load_dwordx4 v[96:99], v[10:11], off
	v_add_co_u32_e32 v10, vcc, s13, v134
	v_lshl_add_u64 v[16:17], v[16:17], 0, v[40:41]
	s_nop 0
	v_addc_co_u32_e32 v11, vcc, 0, v135, vcc
	global_load_dwordx4 v[72:75], v[16:17], off
	global_load_dwordx4 v[108:111], v[10:11], off
	v_add_co_u32_e32 v10, vcc, s38, v14
	v_lshl_add_u64 v[18:19], v[18:19], 0, v[40:41]
	s_nop 0
	v_addc_co_u32_e32 v11, vcc, 0, v15, vcc
	global_load_dwordx4 v[76:79], v[18:19], off
	global_load_dwordx4 v[92:95], v[10:11], off offset:2048
	v_add_co_u32_e32 v10, vcc, s38, v16
	global_load_dwordx4 v[84:87], v[134:135], off
	s_nop 0
	v_addc_co_u32_e32 v11, vcc, 0, v17, vcc
	global_load_dwordx4 v[100:103], v[10:11], off offset:2048
	v_add_co_u32_e32 v10, vcc, s38, v18
	v_and_or_b32 v146, v24, s42, v9
	s_nop 0
	v_addc_co_u32_e32 v11, vcc, 0, v19, vcc
	global_load_dwordx4 v[104:107], v[10:11], off offset:2048
	v_add_co_u32_e32 v10, vcc, s38, v12
	s_cmp_lt_i32 s7, 1
	s_nop 0
	v_addc_co_u32_e32 v11, vcc, 0, v13, vcc
	global_load_dwordx4 v[112:115], v[10:11], off offset:2048
	s_waitcnt vmcnt(9)
	ds_write_b128 v146, v[68:71]
	s_waitcnt vmcnt(7)
	ds_write_b128 v146, v[72:75] offset:4096
	s_waitcnt vmcnt(5)
	ds_write_b128 v146, v[76:79] offset:8192
	ds_write_b128 v146, v[80:83] offset:12288
	s_waitcnt vmcnt(3)
	ds_write_b128 v146, v[84:87] offset:16384
	ds_write_b128 v146, v[88:91] offset:20480
	ds_write_b128 v146, v[96:99] offset:24576
	ds_write_b128 v146, v[108:111] offset:28672
	s_waitcnt lgkmcnt(0)
	s_barrier
	s_cbranch_scc1 .LBB0_127
	v_add_co_u32_e32 v10, vcc, 0x8000, v134
	v_and_b32_e32 v9, 15, v8
	s_nop 0
	v_addc_co_u32_e32 v11, vcc, 0, v135, vcc
	global_load_dwordx4 v[116:119], v[134:135], off offset:128
	global_load_dwordx4 v[120:123], v[10:11], off offset:128
	v_add_co_u32_e32 v10, vcc, 0x10000, v134
	v_lshl_add_u64 v[136:137], v[0:1], 0, v[40:41]
	s_nop 0
	v_addc_co_u32_e32 v11, vcc, 0, v135, vcc
	v_add_co_u32_e32 v12, vcc, 0x18000, v134
	v_mov_b32_e32 v0, 0
	s_nop 0
	v_addc_co_u32_e32 v13, vcc, 0, v135, vcc
	global_load_dwordx4 v[124:127], v[10:11], off offset:128
	global_load_dwordx4 v[128:131], v[12:13], off offset:128
	v_bfe_u32 v10, v8, 1, 3
	v_lshrrev_b32_e32 v11, 4, v8
	v_bfe_u32 v12, v8, 4, 2
	v_lshrrev_b32_e32 v13, 1, v8
	v_lshlrev_b32_e32 v8, 7, v8
	v_and_b32_e32 v8, 0x2780, v8
	v_add_u32_e32 v148, s12, v8
	v_bitop3_b32 v8, v11, v10, 3 bitop3:0x6c
	v_and_or_b32 v9, v13, s39, v9
	v_lshlrev_b32_e32 v149, 4, v8
	v_bitop3_b32 v8, v12, v10, 4 bitop3:0x36
	v_lshl_add_u32 v147, v9, 7, s12
	s_mov_b32 s24, 3
	v_lshlrev_b32_e32 v150, 4, v8
	v_lshl_add_u64 v[138:139], v[2:3], 0, v[40:41]
	v_lshl_add_u64 v[140:141], v[4:5], 0, v[40:41]
	v_lshl_add_u64 v[142:143], v[6:7], 0, v[40:41]
	s_movk_i32 s12, 0xc0
	v_mov_b32_e32 v1, v0
	v_mov_b32_e32 v2, v0
	v_mov_b32_e32 v3, v0
	v_mov_b32_e32 v4, v0
	v_mov_b32_e32 v5, v0
	v_mov_b32_e32 v6, v0
	v_mov_b32_e32 v7, v0
	v_mov_b32_e32 v8, v0
	v_mov_b32_e32 v9, v0
	v_mov_b32_e32 v10, v0
	v_mov_b32_e32 v11, v0
	v_mov_b32_e32 v12, v0
	v_mov_b32_e32 v13, v0
	v_mov_b32_e32 v14, v0
	v_mov_b32_e32 v15, v0
	v_mov_b32_e32 v16, v0
	v_mov_b32_e32 v17, v0
	v_mov_b32_e32 v18, v0
	v_mov_b32_e32 v19, v0
	v_mov_b32_e32 v20, v0
	v_mov_b32_e32 v21, v0
	v_mov_b32_e32 v22, v0
	v_mov_b32_e32 v23, v0
	v_mov_b32_e32 v24, v0
	v_mov_b32_e32 v25, v0
	v_mov_b32_e32 v26, v0
	v_mov_b32_e32 v27, v0
	v_mov_b32_e32 v28, v0
	v_mov_b32_e32 v29, v0
	v_mov_b32_e32 v30, v0
	v_mov_b32_e32 v31, v0
	v_mov_b32_e32 v32, v0
	v_mov_b32_e32 v33, v0
	v_mov_b32_e32 v34, v0
	v_mov_b32_e32 v35, v0
	v_mov_b32_e32 v36, v0
	v_mov_b32_e32 v37, v0
	v_mov_b32_e32 v38, v0
	v_mov_b32_e32 v39, v0
	v_mov_b32_e32 v44, v0
	v_mov_b32_e32 v45, v0
	v_mov_b32_e32 v46, v0
	v_mov_b32_e32 v47, v0
	v_mov_b32_e32 v48, v0
	v_mov_b32_e32 v49, v0
	v_mov_b32_e32 v50, v0
	v_mov_b32_e32 v51, v0
	v_mov_b32_e32 v52, v0
	v_mov_b32_e32 v53, v0
	v_mov_b32_e32 v54, v0
	v_mov_b32_e32 v55, v0
	v_mov_b32_e32 v56, v0
	v_mov_b32_e32 v57, v0
	v_mov_b32_e32 v58, v0
	v_mov_b32_e32 v59, v0
	v_mov_b32_e32 v60, v0
	v_mov_b32_e32 v61, v0
	v_mov_b32_e32 v62, v0
	v_mov_b32_e32 v63, v0
	v_mov_b32_e32 v64, v0
	v_mov_b32_e32 v65, v0
	v_mov_b32_e32 v66, v0
	v_mov_b32_e32 v67, v0
	s_branch .LBB0_121
